# up-projection middle tiles: waves 0-3 start the epilogue without waiting for waves 4-7's last MFMA section (their closing barrier deferred past the epilogue)
# speedup vs baseline: 1.0008x; 1.0008x over previous
.LBB0_362:
	s_ashr_i32 s23, s22, 31
	s_lshl_b64 s[24:25], s[22:23], 19
	s_add_u32 s24, s80, s24
	s_addc_u32 s25, s81, s25
	s_and_b64 s[26:27], s[6:7], exec
	s_cselect_b32 s23, s25, s35
	s_cselect_b32 s39, s24, s34
	s_ashr_i32 s21, s20, 31
	s_lshl_b64 s[26:27], s[20:21], 19
	s_add_u32 s26, s45, s26
	s_addc_u32 s27, s46, s27
	s_and_b64 s[36:37], s[6:7], exec
	s_cselect_b32 s21, s27, s31
	s_cselect_b32 s40, s26, s30
	s_add_u32 s41, s30, 0x100
	s_addc_u32 s43, s31, 0
	s_add_u32 s30, s34, 0x40080
	s_addc_u32 s31, s35, 0
	s_mov_b32 s56, -2
	s_cmp_lg_u64 s[6:7], 0
	s_cselect_b32 s100, 1, 0
	s_cmp_lg_u32 s38, 0
	s_cselect_b32 s100, s100, 0
	s_cmp_lg_u64 s[14:15], 0
	s_cselect_b32 s101, s100, 0
	s_add_u32 s34, s30, 0xfffc0080
	s_addc_u32 s35, s31, -1
	s_add_i32 s57, 0, 0x10000
	s_cmp_eq_u32 s56, 12
	s_cselect_b32 s37, s23, s35
	s_cselect_b32 s36, s39, s34
	v_add_u32_e32 v146, s57, v155
	s_cselect_b32 s35, s21, s43
	s_cselect_b32 s34, s40, s41
	s_cselect_b32 s62, s101, 0
	s_add_i32 s60, 0, 0x14000
	ds_read_b128 v[142:145], v146
	ds_read_b128 v[168:171], v146 offset:1024
	ds_read_b128 v[172:175], v146 offset:2048
	ds_read_b128 v[176:179], v146 offset:3072
	v_add_u32_e32 v146, s60, v155
	ds_read_b128 v[180:183], v146
	ds_read_b128 v[184:187], v146 offset:1024
	ds_read_b128 v[188:191], v146 offset:2048
	ds_read_b128 v[192:195], v146 offset:3072
	v_lshl_add_u64 v[146:147], s[30:31], 0, v[140:141]
	s_add_i32 m0, s48, 0xc000
	ds_read_b128 v[196:199], v157
	ds_read_b128 v[200:203], v157 offset:1024
	ds_read_b128 v[204:207], v157 offset:2048
	ds_read_b128 v[220:223], v157 offset:3072
	ds_read_b128 v[236:239], v157 offset:4096
	ds_read_b128 v[240:243], v157 offset:5120
	ds_read_b128 v[244:247], v157 offset:6144
	ds_read_b128 v[248:251], v157 offset:7168
	global_load_lds_dwordx4 v[146:147], off
	v_lshl_add_u64 v[146:147], s[30:31], 0, v[138:139]
	s_add_i32 m0, s48, 0xe000
	s_nop 0
	global_load_lds_dwordx4 v[146:147], off
	s_nop 0
	s_nop 0
	s_nop 0
	s_nop 0
	s_nop 0
	s_nop 0
	s_nop 0
	s_nop 0
	s_nop 0
	s_nop 0
	s_nop 0
	s_nop 0
	s_nop 0
	s_nop 0
	s_waitcnt vmcnt(8)
	s_waitcnt lgkmcnt(0)
	s_barrier
	s_waitcnt lgkmcnt(0)
	v_mfma_f32_16x16x32_bf16 v[126:129], v[142:145], v[196:199], 0
	v_mfma_f32_16x16x32_bf16 v[118:121], v[172:175], v[196:199], 0
	v_mfma_f32_16x16x32_bf16 v[110:113], v[142:145], v[204:207], 0
	v_mfma_f32_16x16x32_bf16 v[102:105], v[172:175], v[204:207], 0
	v_mfma_f32_16x16x32_bf16 v[94:97], v[142:145], v[236:239], 0
	v_mfma_f32_16x16x32_bf16 v[86:89], v[172:175], v[236:239], 0
	v_mfma_f32_16x16x32_bf16 v[78:81], v[142:145], v[244:247], 0
	v_mfma_f32_16x16x32_bf16 v[70:73], v[172:175], v[244:247], 0
	v_mfma_f32_16x16x32_bf16 v[126:129], v[168:171], v[200:203], v[126:129]
	v_mfma_f32_16x16x32_bf16 v[118:121], v[176:179], v[200:203], v[118:121]
	v_mfma_f32_16x16x32_bf16 v[110:113], v[168:171], v[220:223], v[110:113]
	v_mfma_f32_16x16x32_bf16 v[102:105], v[176:179], v[220:223], v[102:105]
	v_mfma_f32_16x16x32_bf16 v[94:97], v[168:171], v[240:243], v[94:97]
	v_mfma_f32_16x16x32_bf16 v[86:89], v[176:179], v[240:243], v[86:89]
	v_mfma_f32_16x16x32_bf16 v[78:81], v[168:171], v[248:251], v[78:81]
	v_mfma_f32_16x16x32_bf16 v[70:73], v[176:179], v[248:251], v[70:73]
	v_mfma_f32_16x16x32_bf16 v[122:125], v[180:183], v[196:199], 0
	v_mfma_f32_16x16x32_bf16 v[114:117], v[188:191], v[196:199], 0
	v_mfma_f32_16x16x32_bf16 v[106:109], v[180:183], v[204:207], 0
	v_mfma_f32_16x16x32_bf16 v[98:101], v[188:191], v[204:207], 0
	v_mfma_f32_16x16x32_bf16 v[90:93], v[180:183], v[236:239], 0
	v_mfma_f32_16x16x32_bf16 v[82:85], v[188:191], v[236:239], 0
	v_mfma_f32_16x16x32_bf16 v[74:77], v[180:183], v[244:247], 0
	v_mfma_f32_16x16x32_bf16 v[66:69], v[188:191], v[244:247], 0
	v_mfma_f32_16x16x32_bf16 v[122:125], v[184:187], v[200:203], v[122:125]
	v_mfma_f32_16x16x32_bf16 v[114:117], v[192:195], v[200:203], v[114:117]
	v_mfma_f32_16x16x32_bf16 v[106:109], v[184:187], v[220:223], v[106:109]
	v_mfma_f32_16x16x32_bf16 v[98:101], v[192:195], v[220:223], v[98:101]
	v_mfma_f32_16x16x32_bf16 v[90:93], v[184:187], v[240:243], v[90:93]
	v_mfma_f32_16x16x32_bf16 v[82:85], v[192:195], v[240:243], v[82:85]
	v_mfma_f32_16x16x32_bf16 v[74:77], v[184:187], v[248:251], v[74:77]
	v_mfma_f32_16x16x32_bf16 v[66:69], v[192:195], v[248:251], v[66:69]
	s_barrier
	s_add_i32 s57, s57, s44
	v_lshl_add_u64 v[146:147], s[34:35], 0, v[134:135]
	s_mov_b32 m0, s57
	ds_read_b128 v[196:199], v157 offset:16384
	ds_read_b128 v[200:203], v157 offset:17408
	ds_read_b128 v[204:207], v157 offset:18432
	ds_read_b128 v[220:223], v157 offset:19456
	ds_read_b128 v[236:239], v157 offset:20480
	ds_read_b128 v[240:243], v157 offset:21504
	ds_read_b128 v[244:247], v157 offset:22528
	ds_read_b128 v[248:251], v157 offset:23552
	global_load_lds_dwordx4 v[146:147], off
	s_add_i32 m0, s57, 0x2000
	s_add_u32 s58, s34, 0x40000
	v_lshl_add_u64 v[208:209], s[34:35], 0, v[130:131]
	s_addc_u32 s59, s35, 0
	s_add_i32 s57, s60, s44
	global_load_lds_dwordx4 v[208:209], off
	v_lshl_add_u64 v[224:225], s[58:59], 0, v[134:135]
	s_mov_b32 m0, s57
	v_lshl_add_u64 v[230:231], s[36:37], 0, v[132:133]
	global_load_lds_dwordx4 v[224:225], off
	v_lshl_add_u64 v[224:225], s[58:59], 0, v[130:131]
	s_add_i32 m0, s57, 0x2000
	s_nop 0
	global_load_lds_dwordx4 v[224:225], off
	v_lshl_add_u64 v[224:225], s[36:37], 0, v[136:137]
	s_mov_b32 m0, s48
	s_nop 0
	global_load_lds_dwordx4 v[224:225], off
	s_mov_b32 m0, s49
	s_nop 0
	global_load_lds_dwordx4 v[230:231], off
	s_nop 0
	s_nop 0
	s_nop 0
	s_waitcnt vmcnt(8)
	s_waitcnt lgkmcnt(0)
	s_barrier
	s_waitcnt lgkmcnt(0)
	v_mfma_f32_16x16x32_bf16 v[62:65], v[142:145], v[196:199], 0
	v_mfma_f32_16x16x32_bf16 v[54:57], v[172:175], v[196:199], 0
	v_mfma_f32_16x16x32_bf16 v[46:49], v[142:145], v[204:207], 0
	v_mfma_f32_16x16x32_bf16 v[38:41], v[172:175], v[204:207], 0
	v_mfma_f32_16x16x32_bf16 v[30:33], v[142:145], v[236:239], 0
	v_mfma_f32_16x16x32_bf16 v[22:25], v[172:175], v[236:239], 0
	v_mfma_f32_16x16x32_bf16 v[14:17], v[142:145], v[244:247], 0
	v_mfma_f32_16x16x32_bf16 v[6:9], v[172:175], v[244:247], 0
	v_mfma_f32_16x16x32_bf16 v[62:65], v[168:171], v[200:203], v[62:65]
	v_mfma_f32_16x16x32_bf16 v[54:57], v[176:179], v[200:203], v[54:57]
	v_mfma_f32_16x16x32_bf16 v[46:49], v[168:171], v[220:223], v[46:49]
	v_mfma_f32_16x16x32_bf16 v[38:41], v[176:179], v[220:223], v[38:41]
	v_mfma_f32_16x16x32_bf16 v[30:33], v[168:171], v[240:243], v[30:33]
	v_mfma_f32_16x16x32_bf16 v[22:25], v[176:179], v[240:243], v[22:25]
	v_mfma_f32_16x16x32_bf16 v[14:17], v[168:171], v[248:251], v[14:17]
	v_mfma_f32_16x16x32_bf16 v[6:9], v[176:179], v[248:251], v[6:9]
	v_mfma_f32_16x16x32_bf16 v[58:61], v[180:183], v[196:199], 0
	v_mfma_f32_16x16x32_bf16 v[50:53], v[188:191], v[196:199], 0
	v_mfma_f32_16x16x32_bf16 v[42:45], v[180:183], v[204:207], 0
	v_mfma_f32_16x16x32_bf16 v[34:37], v[188:191], v[204:207], 0
	v_mfma_f32_16x16x32_bf16 v[26:29], v[180:183], v[236:239], 0
	v_mfma_f32_16x16x32_bf16 v[18:21], v[188:191], v[236:239], 0
	v_mfma_f32_16x16x32_bf16 v[10:13], v[180:183], v[244:247], 0
	v_mfma_f32_16x16x32_bf16 v[2:5], v[188:191], v[244:247], 0
	v_mfma_f32_16x16x32_bf16 v[58:61], v[184:187], v[200:203], v[58:61]
	v_mfma_f32_16x16x32_bf16 v[50:53], v[192:195], v[200:203], v[50:53]
	v_mfma_f32_16x16x32_bf16 v[42:45], v[184:187], v[220:223], v[42:45]
	v_mfma_f32_16x16x32_bf16 v[34:37], v[192:195], v[220:223], v[34:37]
	v_mfma_f32_16x16x32_bf16 v[26:29], v[184:187], v[240:243], v[26:29]
	v_mfma_f32_16x16x32_bf16 v[18:21], v[192:195], v[240:243], v[18:21]
	v_mfma_f32_16x16x32_bf16 v[10:13], v[184:187], v[248:251], v[10:13]
	v_mfma_f32_16x16x32_bf16 v[2:5], v[192:195], v[248:251], v[2:5]
	s_barrier
	s_add_i32 s57, 0, 0x18000
	v_add_u32_e32 v164, s57, v155
	s_add_i32 s58, 0, 0x1c000
	ds_read_b128 v[142:145], v164
	ds_read_b128 v[168:171], v164 offset:1024
	ds_read_b128 v[172:175], v164 offset:2048
	ds_read_b128 v[176:179], v164 offset:3072
	v_add_u32_e32 v164, s58, v155
	ds_read_b128 v[180:183], v164
	ds_read_b128 v[184:187], v164 offset:1024
	ds_read_b128 v[188:191], v164 offset:2048
	ds_read_b128 v[192:195], v164 offset:3072
	s_add_u32 s36, s36, 0x40000
	s_addc_u32 s37, s37, 0
	s_mov_b32 m0, s50
	v_lshl_add_u64 v[252:253], s[36:37], 0, v[136:137]
	ds_read_b128 v[196:199], v157 offset:32768
	ds_read_b128 v[200:203], v157 offset:33792
	ds_read_b128 v[204:207], v157 offset:34816
	ds_read_b128 v[220:223], v157 offset:35840
	ds_read_b128 v[236:239], v157 offset:36864
	ds_read_b128 v[240:243], v157 offset:37888
	ds_read_b128 v[244:247], v157 offset:38912
	ds_read_b128 v[248:251], v157 offset:39936
	global_load_lds_dwordx4 v[252:253], off
	v_lshl_add_u64 v[252:253], s[36:37], 0, v[132:133]
	s_mov_b32 m0, s51
	s_nop 0
	global_load_lds_dwordx4 v[252:253], off
	s_nop 0
	s_nop 0
	s_nop 0
	s_nop 0
	s_nop 0
	s_nop 0
	s_nop 0
	s_waitcnt vmcnt(8)
	s_waitcnt lgkmcnt(0)
	s_barrier
	s_waitcnt lgkmcnt(0)
	v_mfma_f32_16x16x32_bf16 v[126:129], v[142:145], v[196:199], v[126:129]
	v_mfma_f32_16x16x32_bf16 v[118:121], v[172:175], v[196:199], v[118:121]
	v_mfma_f32_16x16x32_bf16 v[110:113], v[142:145], v[204:207], v[110:113]
	v_mfma_f32_16x16x32_bf16 v[102:105], v[172:175], v[204:207], v[102:105]
	v_mfma_f32_16x16x32_bf16 v[94:97], v[142:145], v[236:239], v[94:97]
	v_mfma_f32_16x16x32_bf16 v[86:89], v[172:175], v[236:239], v[86:89]
	v_mfma_f32_16x16x32_bf16 v[78:81], v[142:145], v[244:247], v[78:81]
	v_mfma_f32_16x16x32_bf16 v[70:73], v[172:175], v[244:247], v[70:73]
	v_mfma_f32_16x16x32_bf16 v[126:129], v[168:171], v[200:203], v[126:129]
	v_mfma_f32_16x16x32_bf16 v[118:121], v[176:179], v[200:203], v[118:121]
	v_mfma_f32_16x16x32_bf16 v[110:113], v[168:171], v[220:223], v[110:113]
	v_mfma_f32_16x16x32_bf16 v[102:105], v[176:179], v[220:223], v[102:105]
	v_mfma_f32_16x16x32_bf16 v[94:97], v[168:171], v[240:243], v[94:97]
	v_mfma_f32_16x16x32_bf16 v[86:89], v[176:179], v[240:243], v[86:89]
	v_mfma_f32_16x16x32_bf16 v[78:81], v[168:171], v[248:251], v[78:81]
	v_mfma_f32_16x16x32_bf16 v[70:73], v[176:179], v[248:251], v[70:73]
	v_mfma_f32_16x16x32_bf16 v[122:125], v[180:183], v[196:199], v[122:125]
	v_mfma_f32_16x16x32_bf16 v[114:117], v[188:191], v[196:199], v[114:117]
	v_mfma_f32_16x16x32_bf16 v[106:109], v[180:183], v[204:207], v[106:109]
	v_mfma_f32_16x16x32_bf16 v[98:101], v[188:191], v[204:207], v[98:101]
	v_mfma_f32_16x16x32_bf16 v[90:93], v[180:183], v[236:239], v[90:93]
	v_mfma_f32_16x16x32_bf16 v[82:85], v[188:191], v[236:239], v[82:85]
	v_mfma_f32_16x16x32_bf16 v[74:77], v[180:183], v[244:247], v[74:77]
	v_mfma_f32_16x16x32_bf16 v[66:69], v[188:191], v[244:247], v[66:69]
	v_mfma_f32_16x16x32_bf16 v[122:125], v[184:187], v[200:203], v[122:125]
	v_mfma_f32_16x16x32_bf16 v[114:117], v[192:195], v[200:203], v[114:117]
	v_mfma_f32_16x16x32_bf16 v[106:109], v[184:187], v[220:223], v[106:109]
	v_mfma_f32_16x16x32_bf16 v[98:101], v[192:195], v[220:223], v[98:101]
	v_mfma_f32_16x16x32_bf16 v[90:93], v[184:187], v[240:243], v[90:93]
	v_mfma_f32_16x16x32_bf16 v[82:85], v[192:195], v[240:243], v[82:85]
	v_mfma_f32_16x16x32_bf16 v[74:77], v[184:187], v[248:251], v[74:77]
	v_mfma_f32_16x16x32_bf16 v[66:69], v[192:195], v[248:251], v[66:69]
	s_barrier
	s_add_i32 s36, s57, s44
	v_lshl_add_u64 v[146:147], v[146:147], 0, s[96:97]
	s_mov_b32 m0, s36
	ds_read_b128 v[196:199], v157 offset:49152
	ds_read_b128 v[200:203], v157 offset:50176
	ds_read_b128 v[204:207], v157 offset:51200
	ds_read_b128 v[220:223], v157 offset:52224
	ds_read_b128 v[236:239], v157 offset:53248
	ds_read_b128 v[240:243], v157 offset:54272
	ds_read_b128 v[244:247], v157 offset:55296
	ds_read_b128 v[248:251], v157 offset:56320
	global_load_lds_dwordx4 v[146:147], off
	s_add_i32 m0, s36, 0x2000
	s_add_u32 s34, s34, 0x40080
	v_lshl_add_u64 v[146:147], v[208:209], 0, s[96:97]
	s_addc_u32 s35, s35, 0
	s_add_i32 s36, s58, s44
	global_load_lds_dwordx4 v[146:147], off
	v_lshl_add_u64 v[146:147], s[34:35], 0, v[134:135]
	s_mov_b32 m0, s36
	s_nop 0
	global_load_lds_dwordx4 v[146:147], off
	v_lshl_add_u64 v[146:147], s[34:35], 0, v[130:131]
	s_add_i32 m0, s36, 0x2000
	s_nop 0
	global_load_lds_dwordx4 v[146:147], off
	v_lshl_add_u64 v[146:147], v[224:225], 0, s[96:97]
	s_mov_b32 m0, s52
	s_nop 0
	global_load_lds_dwordx4 v[146:147], off
	v_lshl_add_u64 v[146:147], v[230:231], 0, s[96:97]
	s_mov_b32 m0, s53
	s_nop 0
	global_load_lds_dwordx4 v[146:147], off
	s_nop 0
	s_nop 0
	s_waitcnt vmcnt(8)
	s_waitcnt lgkmcnt(0)
	s_barrier
	s_waitcnt lgkmcnt(0)
	v_mfma_f32_16x16x32_bf16 v[62:65], v[142:145], v[196:199], v[62:65]
	v_mfma_f32_16x16x32_bf16 v[54:57], v[172:175], v[196:199], v[54:57]
	v_mfma_f32_16x16x32_bf16 v[46:49], v[142:145], v[204:207], v[46:49]
	v_mfma_f32_16x16x32_bf16 v[38:41], v[172:175], v[204:207], v[38:41]
	v_mfma_f32_16x16x32_bf16 v[30:33], v[142:145], v[236:239], v[30:33]
	v_mfma_f32_16x16x32_bf16 v[22:25], v[172:175], v[236:239], v[22:25]
	v_mfma_f32_16x16x32_bf16 v[14:17], v[142:145], v[244:247], v[14:17]
	v_mfma_f32_16x16x32_bf16 v[6:9], v[172:175], v[244:247], v[6:9]
	v_mfma_f32_16x16x32_bf16 v[62:65], v[168:171], v[200:203], v[62:65]
	v_mfma_f32_16x16x32_bf16 v[54:57], v[176:179], v[200:203], v[54:57]
	v_mfma_f32_16x16x32_bf16 v[46:49], v[168:171], v[220:223], v[46:49]
	v_mfma_f32_16x16x32_bf16 v[38:41], v[176:179], v[220:223], v[38:41]
	v_mfma_f32_16x16x32_bf16 v[30:33], v[168:171], v[240:243], v[30:33]
	v_mfma_f32_16x16x32_bf16 v[22:25], v[176:179], v[240:243], v[22:25]
	v_mfma_f32_16x16x32_bf16 v[14:17], v[168:171], v[248:251], v[14:17]
	v_mfma_f32_16x16x32_bf16 v[6:9], v[176:179], v[248:251], v[6:9]
	v_mfma_f32_16x16x32_bf16 v[58:61], v[180:183], v[196:199], v[58:61]
	v_mfma_f32_16x16x32_bf16 v[50:53], v[188:191], v[196:199], v[50:53]
	v_mfma_f32_16x16x32_bf16 v[42:45], v[180:183], v[204:207], v[42:45]
	v_mfma_f32_16x16x32_bf16 v[34:37], v[188:191], v[204:207], v[34:37]
	v_mfma_f32_16x16x32_bf16 v[26:29], v[180:183], v[236:239], v[26:29]
	v_mfma_f32_16x16x32_bf16 v[18:21], v[188:191], v[236:239], v[18:21]
	v_mfma_f32_16x16x32_bf16 v[10:13], v[180:183], v[244:247], v[10:13]
	v_mfma_f32_16x16x32_bf16 v[2:5], v[188:191], v[244:247], v[2:5]
	v_mfma_f32_16x16x32_bf16 v[58:61], v[184:187], v[200:203], v[58:61]
	v_mfma_f32_16x16x32_bf16 v[50:53], v[192:195], v[200:203], v[50:53]
	v_mfma_f32_16x16x32_bf16 v[42:45], v[184:187], v[220:223], v[42:45]
	v_mfma_f32_16x16x32_bf16 v[34:37], v[192:195], v[220:223], v[34:37]
	v_mfma_f32_16x16x32_bf16 v[26:29], v[184:187], v[240:243], v[26:29]
	v_mfma_f32_16x16x32_bf16 v[18:21], v[192:195], v[240:243], v[18:21]
	v_mfma_f32_16x16x32_bf16 v[10:13], v[184:187], v[248:251], v[10:13]
	v_mfma_f32_16x16x32_bf16 v[2:5], v[192:195], v[248:251], v[2:5]
	s_barrier
	s_add_i32 s56, s56, 2
	s_add_u32 s41, s41, 0x100
	s_addc_u32 s43, s43, 0
	s_add_u32 s30, s30, 0x100
	s_addc_u32 s31, s31, 0
	s_cmp_gt_u32 s56, 13
.LBB0_363:
	s_add_u32 s34, s30, 0xfffc0080
	s_addc_u32 s35, s31, -1
	s_add_i32 s57, 0, 0x10000
	s_cmp_eq_u32 s56, 12
	s_cselect_b32 s37, s23, s35
	s_cselect_b32 s36, s39, s34
	v_add_u32_e32 v146, s57, v155
	s_cselect_b32 s35, s21, s43
	s_cselect_b32 s34, s40, s41
	s_cselect_b32 s62, s101, 0
	s_add_i32 s60, 0, 0x14000
	ds_read_b128 v[142:145], v146
	ds_read_b128 v[168:171], v146 offset:1024
	ds_read_b128 v[172:175], v146 offset:2048
	ds_read_b128 v[176:179], v146 offset:3072
	v_add_u32_e32 v146, s60, v155
	ds_read_b128 v[180:183], v146
	ds_read_b128 v[184:187], v146 offset:1024
	ds_read_b128 v[188:191], v146 offset:2048
	ds_read_b128 v[192:195], v146 offset:3072
	v_lshl_add_u64 v[146:147], s[30:31], 0, v[140:141]
	s_add_i32 m0, s48, 0xc000
	ds_read_b128 v[196:199], v157
	ds_read_b128 v[200:203], v157 offset:1024
	ds_read_b128 v[204:207], v157 offset:2048
	ds_read_b128 v[220:223], v157 offset:3072
	ds_read_b128 v[236:239], v157 offset:4096
	ds_read_b128 v[240:243], v157 offset:5120
	ds_read_b128 v[244:247], v157 offset:6144
	ds_read_b128 v[248:251], v157 offset:7168
	global_load_lds_dwordx4 v[146:147], off
	v_lshl_add_u64 v[146:147], s[30:31], 0, v[138:139]
	s_add_i32 m0, s48, 0xe000
	s_nop 0
	global_load_lds_dwordx4 v[146:147], off
	s_nop 0
	s_nop 0
	s_nop 0
	s_nop 0
	s_nop 0
	s_nop 0
	s_nop 0
	s_nop 0
	s_nop 0
	s_nop 0
	s_nop 0
	s_nop 0
	s_nop 0
	s_nop 0
	s_nop 0
	s_nop 0
	s_nop 0
	s_nop 0
	s_nop 0
	s_nop 0
	s_nop 0
	s_nop 0
	s_nop 0
	s_waitcnt vmcnt(8)
	s_waitcnt lgkmcnt(0)
	s_barrier
	s_waitcnt lgkmcnt(0)
	v_mfma_f32_16x16x32_bf16 v[126:129], v[142:145], v[196:199], v[126:129]
	v_mfma_f32_16x16x32_bf16 v[118:121], v[172:175], v[196:199], v[118:121]
	v_mfma_f32_16x16x32_bf16 v[110:113], v[142:145], v[204:207], v[110:113]
	v_mfma_f32_16x16x32_bf16 v[102:105], v[172:175], v[204:207], v[102:105]
	v_mfma_f32_16x16x32_bf16 v[94:97], v[142:145], v[236:239], v[94:97]
	v_mfma_f32_16x16x32_bf16 v[86:89], v[172:175], v[236:239], v[86:89]
	v_mfma_f32_16x16x32_bf16 v[78:81], v[142:145], v[244:247], v[78:81]
	v_mfma_f32_16x16x32_bf16 v[70:73], v[172:175], v[244:247], v[70:73]
	v_mfma_f32_16x16x32_bf16 v[126:129], v[168:171], v[200:203], v[126:129]
	v_mfma_f32_16x16x32_bf16 v[118:121], v[176:179], v[200:203], v[118:121]
	v_mfma_f32_16x16x32_bf16 v[110:113], v[168:171], v[220:223], v[110:113]
	v_mfma_f32_16x16x32_bf16 v[102:105], v[176:179], v[220:223], v[102:105]
	v_mfma_f32_16x16x32_bf16 v[94:97], v[168:171], v[240:243], v[94:97]
	v_mfma_f32_16x16x32_bf16 v[86:89], v[176:179], v[240:243], v[86:89]
	v_mfma_f32_16x16x32_bf16 v[78:81], v[168:171], v[248:251], v[78:81]
	v_mfma_f32_16x16x32_bf16 v[70:73], v[176:179], v[248:251], v[70:73]
	v_mfma_f32_16x16x32_bf16 v[122:125], v[180:183], v[196:199], v[122:125]
	v_mfma_f32_16x16x32_bf16 v[114:117], v[188:191], v[196:199], v[114:117]
	v_mfma_f32_16x16x32_bf16 v[106:109], v[180:183], v[204:207], v[106:109]
	v_mfma_f32_16x16x32_bf16 v[98:101], v[188:191], v[204:207], v[98:101]
	v_mfma_f32_16x16x32_bf16 v[90:93], v[180:183], v[236:239], v[90:93]
	v_mfma_f32_16x16x32_bf16 v[82:85], v[188:191], v[236:239], v[82:85]
	v_mfma_f32_16x16x32_bf16 v[74:77], v[180:183], v[244:247], v[74:77]
	v_mfma_f32_16x16x32_bf16 v[66:69], v[188:191], v[244:247], v[66:69]
	v_mfma_f32_16x16x32_bf16 v[122:125], v[184:187], v[200:203], v[122:125]
	v_mfma_f32_16x16x32_bf16 v[114:117], v[192:195], v[200:203], v[114:117]
	v_mfma_f32_16x16x32_bf16 v[106:109], v[184:187], v[220:223], v[106:109]
	v_mfma_f32_16x16x32_bf16 v[98:101], v[192:195], v[220:223], v[98:101]
	v_mfma_f32_16x16x32_bf16 v[90:93], v[184:187], v[240:243], v[90:93]
	v_mfma_f32_16x16x32_bf16 v[82:85], v[192:195], v[240:243], v[82:85]
	v_mfma_f32_16x16x32_bf16 v[74:77], v[184:187], v[248:251], v[74:77]
	v_mfma_f32_16x16x32_bf16 v[66:69], v[192:195], v[248:251], v[66:69]
	s_barrier
	s_add_i32 s57, s57, s44
	v_lshl_add_u64 v[146:147], s[34:35], 0, v[134:135]
	s_mov_b32 m0, s57
	ds_read_b128 v[196:199], v157 offset:16384
	ds_read_b128 v[200:203], v157 offset:17408
	ds_read_b128 v[204:207], v157 offset:18432
	ds_read_b128 v[220:223], v157 offset:19456
	ds_read_b128 v[236:239], v157 offset:20480
	ds_read_b128 v[240:243], v157 offset:21504
	ds_read_b128 v[244:247], v157 offset:22528
	ds_read_b128 v[248:251], v157 offset:23552
	global_load_lds_dwordx4 v[146:147], off
	s_add_i32 m0, s57, 0x2000
	s_add_u32 s58, s34, 0x40000
	v_lshl_add_u64 v[208:209], s[34:35], 0, v[130:131]
	s_addc_u32 s59, s35, 0
	s_add_i32 s57, s60, s44
	global_load_lds_dwordx4 v[208:209], off
	v_lshl_add_u64 v[224:225], s[58:59], 0, v[134:135]
	s_mov_b32 m0, s57
	v_lshl_add_u64 v[230:231], s[36:37], 0, v[132:133]
	global_load_lds_dwordx4 v[224:225], off
	v_lshl_add_u64 v[224:225], s[58:59], 0, v[130:131]
	s_add_i32 m0, s57, 0x2000
	s_nop 0
	global_load_lds_dwordx4 v[224:225], off
	v_lshl_add_u64 v[224:225], s[36:37], 0, v[136:137]
	s_mov_b32 m0, s48
	s_nop 0
	global_load_lds_dwordx4 v[224:225], off
	s_mov_b32 m0, s49
	s_nop 0
	global_load_lds_dwordx4 v[230:231], off
	s_nop 0
	s_nop 0
	s_nop 0
	s_waitcnt vmcnt(8)
	s_waitcnt lgkmcnt(0)
	s_barrier
	s_waitcnt lgkmcnt(0)
	v_mfma_f32_16x16x32_bf16 v[62:65], v[142:145], v[196:199], v[62:65]
	v_mfma_f32_16x16x32_bf16 v[54:57], v[172:175], v[196:199], v[54:57]
	v_mfma_f32_16x16x32_bf16 v[46:49], v[142:145], v[204:207], v[46:49]
	v_mfma_f32_16x16x32_bf16 v[38:41], v[172:175], v[204:207], v[38:41]
	v_mfma_f32_16x16x32_bf16 v[30:33], v[142:145], v[236:239], v[30:33]
	v_mfma_f32_16x16x32_bf16 v[22:25], v[172:175], v[236:239], v[22:25]
	v_mfma_f32_16x16x32_bf16 v[14:17], v[142:145], v[244:247], v[14:17]
	v_mfma_f32_16x16x32_bf16 v[6:9], v[172:175], v[244:247], v[6:9]
	v_mfma_f32_16x16x32_bf16 v[62:65], v[168:171], v[200:203], v[62:65]
	v_mfma_f32_16x16x32_bf16 v[54:57], v[176:179], v[200:203], v[54:57]
	v_mfma_f32_16x16x32_bf16 v[46:49], v[168:171], v[220:223], v[46:49]
	v_mfma_f32_16x16x32_bf16 v[38:41], v[176:179], v[220:223], v[38:41]
	v_mfma_f32_16x16x32_bf16 v[30:33], v[168:171], v[240:243], v[30:33]
	v_mfma_f32_16x16x32_bf16 v[22:25], v[176:179], v[240:243], v[22:25]
	v_mfma_f32_16x16x32_bf16 v[14:17], v[168:171], v[248:251], v[14:17]
	v_mfma_f32_16x16x32_bf16 v[6:9], v[176:179], v[248:251], v[6:9]
	v_mfma_f32_16x16x32_bf16 v[58:61], v[180:183], v[196:199], v[58:61]
	v_mfma_f32_16x16x32_bf16 v[50:53], v[188:191], v[196:199], v[50:53]
	v_mfma_f32_16x16x32_bf16 v[42:45], v[180:183], v[204:207], v[42:45]
	v_mfma_f32_16x16x32_bf16 v[34:37], v[188:191], v[204:207], v[34:37]
	v_mfma_f32_16x16x32_bf16 v[26:29], v[180:183], v[236:239], v[26:29]
	v_mfma_f32_16x16x32_bf16 v[18:21], v[188:191], v[236:239], v[18:21]
	v_mfma_f32_16x16x32_bf16 v[10:13], v[180:183], v[244:247], v[10:13]
	v_mfma_f32_16x16x32_bf16 v[2:5], v[188:191], v[244:247], v[2:5]
	v_mfma_f32_16x16x32_bf16 v[58:61], v[184:187], v[200:203], v[58:61]
	v_mfma_f32_16x16x32_bf16 v[50:53], v[192:195], v[200:203], v[50:53]
	v_mfma_f32_16x16x32_bf16 v[42:45], v[184:187], v[220:223], v[42:45]
	v_mfma_f32_16x16x32_bf16 v[34:37], v[192:195], v[220:223], v[34:37]
	v_mfma_f32_16x16x32_bf16 v[26:29], v[184:187], v[240:243], v[26:29]
	v_mfma_f32_16x16x32_bf16 v[18:21], v[192:195], v[240:243], v[18:21]
	v_mfma_f32_16x16x32_bf16 v[10:13], v[184:187], v[248:251], v[10:13]
	v_mfma_f32_16x16x32_bf16 v[2:5], v[192:195], v[248:251], v[2:5]
	s_barrier
	s_add_i32 s57, 0, 0x18000
	v_add_u32_e32 v164, s57, v155
	s_add_i32 s58, 0, 0x1c000
	ds_read_b128 v[142:145], v164
	ds_read_b128 v[168:171], v164 offset:1024
	ds_read_b128 v[172:175], v164 offset:2048
	ds_read_b128 v[176:179], v164 offset:3072
	v_add_u32_e32 v164, s58, v155
	ds_read_b128 v[180:183], v164
	ds_read_b128 v[184:187], v164 offset:1024
	ds_read_b128 v[188:191], v164 offset:2048
	ds_read_b128 v[192:195], v164 offset:3072
	s_add_u32 s36, s36, 0x40000
	s_addc_u32 s37, s37, 0
	s_mov_b32 m0, s50
	v_lshl_add_u64 v[252:253], s[36:37], 0, v[136:137]
	ds_read_b128 v[196:199], v157 offset:32768
	ds_read_b128 v[200:203], v157 offset:33792
	ds_read_b128 v[204:207], v157 offset:34816
	ds_read_b128 v[220:223], v157 offset:35840
	ds_read_b128 v[236:239], v157 offset:36864
	ds_read_b128 v[240:243], v157 offset:37888
	ds_read_b128 v[244:247], v157 offset:38912
	ds_read_b128 v[248:251], v157 offset:39936
	global_load_lds_dwordx4 v[252:253], off
	v_lshl_add_u64 v[252:253], s[36:37], 0, v[132:133]
	s_mov_b32 m0, s51
	s_nop 0
	global_load_lds_dwordx4 v[252:253], off
	s_nop 0
	s_nop 0
	s_nop 0
	s_nop 0
	s_nop 0
	s_nop 0
	s_nop 0
	s_waitcnt vmcnt(8)
	s_waitcnt lgkmcnt(0)
	s_barrier
	s_waitcnt lgkmcnt(0)
	v_mfma_f32_16x16x32_bf16 v[126:129], v[142:145], v[196:199], v[126:129]
	v_mfma_f32_16x16x32_bf16 v[118:121], v[172:175], v[196:199], v[118:121]
	v_mfma_f32_16x16x32_bf16 v[110:113], v[142:145], v[204:207], v[110:113]
	v_mfma_f32_16x16x32_bf16 v[102:105], v[172:175], v[204:207], v[102:105]
	v_mfma_f32_16x16x32_bf16 v[94:97], v[142:145], v[236:239], v[94:97]
	v_mfma_f32_16x16x32_bf16 v[86:89], v[172:175], v[236:239], v[86:89]
	v_mfma_f32_16x16x32_bf16 v[78:81], v[142:145], v[244:247], v[78:81]
	v_mfma_f32_16x16x32_bf16 v[70:73], v[172:175], v[244:247], v[70:73]
	v_mfma_f32_16x16x32_bf16 v[126:129], v[168:171], v[200:203], v[126:129]
	v_mfma_f32_16x16x32_bf16 v[118:121], v[176:179], v[200:203], v[118:121]
	v_mfma_f32_16x16x32_bf16 v[110:113], v[168:171], v[220:223], v[110:113]
	v_mfma_f32_16x16x32_bf16 v[102:105], v[176:179], v[220:223], v[102:105]
	v_mfma_f32_16x16x32_bf16 v[94:97], v[168:171], v[240:243], v[94:97]
	v_mfma_f32_16x16x32_bf16 v[86:89], v[176:179], v[240:243], v[86:89]
	v_mfma_f32_16x16x32_bf16 v[78:81], v[168:171], v[248:251], v[78:81]
	v_mfma_f32_16x16x32_bf16 v[70:73], v[176:179], v[248:251], v[70:73]
	v_mfma_f32_16x16x32_bf16 v[122:125], v[180:183], v[196:199], v[122:125]
	v_mfma_f32_16x16x32_bf16 v[114:117], v[188:191], v[196:199], v[114:117]
	v_mfma_f32_16x16x32_bf16 v[106:109], v[180:183], v[204:207], v[106:109]
	v_mfma_f32_16x16x32_bf16 v[98:101], v[188:191], v[204:207], v[98:101]
	v_mfma_f32_16x16x32_bf16 v[90:93], v[180:183], v[236:239], v[90:93]
	v_mfma_f32_16x16x32_bf16 v[82:85], v[188:191], v[236:239], v[82:85]
	v_mfma_f32_16x16x32_bf16 v[74:77], v[180:183], v[244:247], v[74:77]
	v_mfma_f32_16x16x32_bf16 v[66:69], v[188:191], v[244:247], v[66:69]
	v_mfma_f32_16x16x32_bf16 v[122:125], v[184:187], v[200:203], v[122:125]
	v_mfma_f32_16x16x32_bf16 v[114:117], v[192:195], v[200:203], v[114:117]
	v_mfma_f32_16x16x32_bf16 v[106:109], v[184:187], v[220:223], v[106:109]
	v_mfma_f32_16x16x32_bf16 v[98:101], v[192:195], v[220:223], v[98:101]
	v_mfma_f32_16x16x32_bf16 v[90:93], v[184:187], v[240:243], v[90:93]
	v_mfma_f32_16x16x32_bf16 v[82:85], v[192:195], v[240:243], v[82:85]
	v_mfma_f32_16x16x32_bf16 v[74:77], v[184:187], v[248:251], v[74:77]
	v_mfma_f32_16x16x32_bf16 v[66:69], v[192:195], v[248:251], v[66:69]
	s_barrier
	s_add_i32 s36, s57, s44
	v_lshl_add_u64 v[146:147], v[146:147], 0, s[96:97]
	s_mov_b32 m0, s36
	ds_read_b128 v[196:199], v157 offset:49152
	ds_read_b128 v[200:203], v157 offset:50176
	ds_read_b128 v[204:207], v157 offset:51200
	ds_read_b128 v[220:223], v157 offset:52224
	ds_read_b128 v[236:239], v157 offset:53248
	ds_read_b128 v[240:243], v157 offset:54272
	ds_read_b128 v[244:247], v157 offset:55296
	ds_read_b128 v[248:251], v157 offset:56320
	global_load_lds_dwordx4 v[146:147], off
	s_add_i32 m0, s36, 0x2000
	s_add_u32 s34, s34, 0x40080
	v_lshl_add_u64 v[146:147], v[208:209], 0, s[96:97]
	s_addc_u32 s35, s35, 0
	s_add_i32 s36, s58, s44
	global_load_lds_dwordx4 v[146:147], off
	v_lshl_add_u64 v[146:147], s[34:35], 0, v[134:135]
	s_mov_b32 m0, s36
	s_nop 0
	global_load_lds_dwordx4 v[146:147], off
	v_lshl_add_u64 v[146:147], s[34:35], 0, v[130:131]
	s_add_i32 m0, s36, 0x2000
	s_nop 0
	global_load_lds_dwordx4 v[146:147], off
	v_lshl_add_u64 v[146:147], v[224:225], 0, s[96:97]
	s_mov_b32 m0, s52
	s_nop 0
	global_load_lds_dwordx4 v[146:147], off
	v_lshl_add_u64 v[146:147], v[230:231], 0, s[96:97]
	s_mov_b32 m0, s53
	s_nop 0
	global_load_lds_dwordx4 v[146:147], off
	s_nop 0
	s_nop 0
	s_nop 0
	s_nop 0
	s_nop 0
	s_nop 0
	s_nop 0
	s_nop 0
	s_nop 0
	s_nop 0
	s_nop 0
	s_nop 0
	s_nop 0
	s_nop 0
	s_nop 0
	s_nop 0
	s_nop 0
	s_waitcnt vmcnt(8)
	s_waitcnt lgkmcnt(0)
	s_barrier
	s_waitcnt lgkmcnt(0)
	s_bitcmp1_b32 s62, 0
	v_mfma_f32_16x16x32_bf16 v[62:65], v[142:145], v[196:199], v[62:65]
	v_mfma_f32_16x16x32_bf16 v[54:57], v[172:175], v[196:199], v[54:57]
	v_mfma_f32_16x16x32_bf16 v[46:49], v[142:145], v[204:207], v[46:49]
	v_mfma_f32_16x16x32_bf16 v[38:41], v[172:175], v[204:207], v[38:41]
	v_mfma_f32_16x16x32_bf16 v[30:33], v[142:145], v[236:239], v[30:33]
	v_mfma_f32_16x16x32_bf16 v[22:25], v[172:175], v[236:239], v[22:25]
	v_mfma_f32_16x16x32_bf16 v[14:17], v[142:145], v[244:247], v[14:17]
	v_mfma_f32_16x16x32_bf16 v[6:9], v[172:175], v[244:247], v[6:9]
	v_mfma_f32_16x16x32_bf16 v[62:65], v[168:171], v[200:203], v[62:65]
	v_mfma_f32_16x16x32_bf16 v[54:57], v[176:179], v[200:203], v[54:57]
	v_mfma_f32_16x16x32_bf16 v[46:49], v[168:171], v[220:223], v[46:49]
	v_mfma_f32_16x16x32_bf16 v[38:41], v[176:179], v[220:223], v[38:41]
	v_mfma_f32_16x16x32_bf16 v[30:33], v[168:171], v[240:243], v[30:33]
	v_mfma_f32_16x16x32_bf16 v[22:25], v[176:179], v[240:243], v[22:25]
	v_mfma_f32_16x16x32_bf16 v[14:17], v[168:171], v[248:251], v[14:17]
	v_mfma_f32_16x16x32_bf16 v[6:9], v[176:179], v[248:251], v[6:9]
	v_mfma_f32_16x16x32_bf16 v[58:61], v[180:183], v[196:199], v[58:61]
	v_mfma_f32_16x16x32_bf16 v[50:53], v[188:191], v[196:199], v[50:53]
	v_mfma_f32_16x16x32_bf16 v[42:45], v[180:183], v[204:207], v[42:45]
	v_mfma_f32_16x16x32_bf16 v[34:37], v[188:191], v[204:207], v[34:37]
	v_mfma_f32_16x16x32_bf16 v[26:29], v[180:183], v[236:239], v[26:29]
	v_mfma_f32_16x16x32_bf16 v[18:21], v[188:191], v[236:239], v[18:21]
	v_mfma_f32_16x16x32_bf16 v[10:13], v[180:183], v[244:247], v[10:13]
	v_mfma_f32_16x16x32_bf16 v[2:5], v[188:191], v[244:247], v[2:5]
	v_mfma_f32_16x16x32_bf16 v[58:61], v[184:187], v[200:203], v[58:61]
	v_mfma_f32_16x16x32_bf16 v[50:53], v[192:195], v[200:203], v[50:53]
	v_mfma_f32_16x16x32_bf16 v[42:45], v[184:187], v[220:223], v[42:45]
	v_mfma_f32_16x16x32_bf16 v[34:37], v[192:195], v[220:223], v[34:37]
	v_mfma_f32_16x16x32_bf16 v[26:29], v[184:187], v[240:243], v[26:29]
	v_mfma_f32_16x16x32_bf16 v[18:21], v[192:195], v[240:243], v[18:21]
	v_mfma_f32_16x16x32_bf16 v[10:13], v[184:187], v[248:251], v[10:13]
	v_mfma_f32_16x16x32_bf16 v[2:5], v[192:195], v[248:251], v[2:5]
	s_cbranch_scc1 .Lsw_nobar
	s_barrier
.Lsw_nobar:
	s_add_i32 s56, s56, 2
	s_add_u32 s41, s41, 0x100
	s_addc_u32 s43, s43, 0
	s_add_u32 s30, s30, 0x100
	s_addc_u32 s31, s31, 0
	s_cmp_gt_u32 s56, 13
	s_cbranch_scc0 .LBB0_363
	s_cmp_lg_u32 s100, 0
	s_cbranch_scc1 .LBB0_366
	s_and_b64 vcc, exec, s[16:17]
	s_cbranch_vccz .LBB0_366
	s_barrier

.LBB0_476:
	s_add_i32 s63, s31, 2
	s_add_u32 s38, s28, s36
	s_addc_u32 s39, s29, s37
	s_add_u32 s64, s26, s36
	s_addc_u32 s65, s27, s37
	s_add_i32 s66, 0, 0x10000
	s_cmp_eq_u32 s59, s31
	s_cselect_b32 s39, s9, s39
	s_cselect_b32 s38, s8, s38
	s_cselect_b32 s65, s35, s65
	s_cselect_b32 s64, s34, s64
	s_add_i32 s31, 0, 0x14000
	v_add_u32_e32 v160, s66, v146
	v_add_u32_e32 v176, s31, v146
	ds_read_b128 v[148:151], v160
	ds_read_b128 v[152:155], v160 offset:1024
	ds_read_b128 v[156:159], v160 offset:2048
	ds_read_b128 v[160:163], v160 offset:3072
	ds_read_b128 v[164:167], v176
	ds_read_b128 v[168:171], v176 offset:1024
	ds_read_b128 v[172:175], v176 offset:2048
	ds_read_b128 v[176:179], v176 offset:3072
	v_lshl_add_u64 v[208:209], s[28:29], 0, v[142:143]
	s_add_i32 m0, s51, 0xc000
	ds_read_b128 v[180:183], v147
	ds_read_b128 v[184:187], v147 offset:1024
	ds_read_b128 v[188:191], v147 offset:2048
	ds_read_b128 v[192:195], v147 offset:3072
	ds_read_b128 v[196:199], v147 offset:4096
	ds_read_b128 v[200:203], v147 offset:5120
	ds_read_b128 v[204:207], v147 offset:6144
	ds_read_b128 v[220:223], v147 offset:7168
	global_load_lds_dwordx4 v[208:209], off
	v_lshl_add_u64 v[208:209], s[28:29], 0, v[144:145]
	s_add_i32 m0, s51, 0xe000
	s_nop 0
	global_load_lds_dwordx4 v[208:209], off
	s_nop 0
	s_nop 0
	s_nop 0
	s_nop 0
	s_nop 0
	s_nop 0
	s_nop 0
	s_nop 0
	s_nop 0
	s_nop 0
	s_nop 0
	s_nop 0
	s_nop 0
	s_nop 0
	s_nop 0
	s_nop 0
	s_nop 0
	s_nop 0
	s_nop 0
	s_nop 0
	s_nop 0
	s_nop 0
	s_nop 0
	s_nop 0
	s_nop 0
	s_waitcnt vmcnt(8)
	s_waitcnt lgkmcnt(0)
	s_barrier
	s_waitcnt lgkmcnt(0)
	v_mfma_f32_16x16x32_bf16 v[126:129], v[148:151], v[180:183], v[126:129]
	v_mfma_f32_16x16x32_bf16 v[122:125], v[156:159], v[180:183], v[122:125]
	v_mfma_f32_16x16x32_bf16 v[110:113], v[148:151], v[188:191], v[110:113]
	v_mfma_f32_16x16x32_bf16 v[106:109], v[156:159], v[188:191], v[106:109]
	v_mfma_f32_16x16x32_bf16 v[94:97], v[148:151], v[196:199], v[94:97]
	v_mfma_f32_16x16x32_bf16 v[90:93], v[156:159], v[196:199], v[90:93]
	v_mfma_f32_16x16x32_bf16 v[78:81], v[148:151], v[204:207], v[78:81]
	v_mfma_f32_16x16x32_bf16 v[74:77], v[156:159], v[204:207], v[74:77]
	v_mfma_f32_16x16x32_bf16 v[126:129], v[152:155], v[184:187], v[126:129]
	v_mfma_f32_16x16x32_bf16 v[122:125], v[160:163], v[184:187], v[122:125]
	v_mfma_f32_16x16x32_bf16 v[110:113], v[152:155], v[192:195], v[110:113]
	v_mfma_f32_16x16x32_bf16 v[106:109], v[160:163], v[192:195], v[106:109]
	v_mfma_f32_16x16x32_bf16 v[94:97], v[152:155], v[200:203], v[94:97]
	v_mfma_f32_16x16x32_bf16 v[90:93], v[160:163], v[200:203], v[90:93]
	v_mfma_f32_16x16x32_bf16 v[78:81], v[152:155], v[220:223], v[78:81]
	v_mfma_f32_16x16x32_bf16 v[74:77], v[160:163], v[220:223], v[74:77]
	v_mfma_f32_16x16x32_bf16 v[118:121], v[164:167], v[180:183], v[118:121]
	v_mfma_f32_16x16x32_bf16 v[114:117], v[172:175], v[180:183], v[114:117]
	v_mfma_f32_16x16x32_bf16 v[102:105], v[164:167], v[188:191], v[102:105]
	v_mfma_f32_16x16x32_bf16 v[98:101], v[172:175], v[188:191], v[98:101]
	v_mfma_f32_16x16x32_bf16 v[86:89], v[164:167], v[196:199], v[86:89]
	v_mfma_f32_16x16x32_bf16 v[82:85], v[172:175], v[196:199], v[82:85]
	v_mfma_f32_16x16x32_bf16 v[70:73], v[164:167], v[204:207], v[70:73]
	v_mfma_f32_16x16x32_bf16 v[66:69], v[172:175], v[204:207], v[66:69]
	v_mfma_f32_16x16x32_bf16 v[118:121], v[168:171], v[184:187], v[118:121]
	v_mfma_f32_16x16x32_bf16 v[114:117], v[176:179], v[184:187], v[114:117]
	v_mfma_f32_16x16x32_bf16 v[102:105], v[168:171], v[192:195], v[102:105]
	v_mfma_f32_16x16x32_bf16 v[98:101], v[176:179], v[192:195], v[98:101]
	v_mfma_f32_16x16x32_bf16 v[86:89], v[168:171], v[200:203], v[86:89]
	v_mfma_f32_16x16x32_bf16 v[82:85], v[176:179], v[200:203], v[82:85]
	v_mfma_f32_16x16x32_bf16 v[70:73], v[168:171], v[220:223], v[70:73]
	v_mfma_f32_16x16x32_bf16 v[66:69], v[176:179], v[220:223], v[66:69]
	s_barrier
	s_add_i32 s66, s66, s47
	v_lshl_add_u64 v[208:209], s[64:65], 0, v[132:133]
	s_mov_b32 m0, s66
	ds_read_b128 v[180:183], v147 offset:16384
	ds_read_b128 v[184:187], v147 offset:17408
	ds_read_b128 v[188:191], v147 offset:18432
	ds_read_b128 v[192:195], v147 offset:19456
	ds_read_b128 v[196:199], v147 offset:20480
	ds_read_b128 v[200:203], v147 offset:21504
	ds_read_b128 v[204:207], v147 offset:22528
	ds_read_b128 v[220:223], v147 offset:23552
	global_load_lds_dwordx4 v[208:209], off
	s_add_i32 m0, s66, 0x2000
	v_lshl_add_u64 v[224:225], s[64:65], 0, v[136:137]
	s_add_u32 s64, s64, s45
	s_addc_u32 s65, s65, 0
	s_add_i32 s31, s31, s47
	global_load_lds_dwordx4 v[224:225], off
	v_lshl_add_u64 v[230:231], s[64:65], 0, v[132:133]
	s_mov_b32 m0, s31
	v_lshl_add_u64 v[236:237], s[64:65], 0, v[136:137]
	global_load_lds_dwordx4 v[230:231], off
	s_add_i32 m0, s31, 0x2000
	v_lshl_add_u64 v[238:239], s[38:39], 0, v[130:131]
	global_load_lds_dwordx4 v[236:237], off
	s_mov_b32 m0, s51
	v_lshl_add_u64 v[240:241], s[38:39], 0, v[134:135]
	global_load_lds_dwordx4 v[238:239], off
	s_mov_b32 m0, s52
	s_nop 0
	global_load_lds_dwordx4 v[240:241], off
	s_nop 0
	s_nop 0
	s_nop 0
	s_nop 0
	s_nop 0
	s_nop 0
	s_waitcnt vmcnt(8)
	s_waitcnt lgkmcnt(0)
	s_barrier
	s_waitcnt lgkmcnt(0)
	v_mfma_f32_16x16x32_bf16 v[62:65], v[148:151], v[180:183], v[62:65]
	v_mfma_f32_16x16x32_bf16 v[58:61], v[156:159], v[180:183], v[58:61]
	v_mfma_f32_16x16x32_bf16 v[46:49], v[148:151], v[188:191], v[46:49]
	v_mfma_f32_16x16x32_bf16 v[42:45], v[156:159], v[188:191], v[42:45]
	v_mfma_f32_16x16x32_bf16 v[30:33], v[148:151], v[196:199], v[30:33]
	v_mfma_f32_16x16x32_bf16 v[26:29], v[156:159], v[196:199], v[26:29]
	v_mfma_f32_16x16x32_bf16 v[14:17], v[148:151], v[204:207], v[14:17]
	v_mfma_f32_16x16x32_bf16 v[10:13], v[156:159], v[204:207], v[10:13]
	v_mfma_f32_16x16x32_bf16 v[62:65], v[152:155], v[184:187], v[62:65]
	v_mfma_f32_16x16x32_bf16 v[58:61], v[160:163], v[184:187], v[58:61]
	v_mfma_f32_16x16x32_bf16 v[46:49], v[152:155], v[192:195], v[46:49]
	v_mfma_f32_16x16x32_bf16 v[42:45], v[160:163], v[192:195], v[42:45]
	v_mfma_f32_16x16x32_bf16 v[30:33], v[152:155], v[200:203], v[30:33]
	v_mfma_f32_16x16x32_bf16 v[26:29], v[160:163], v[200:203], v[26:29]
	v_mfma_f32_16x16x32_bf16 v[14:17], v[152:155], v[220:223], v[14:17]
	v_mfma_f32_16x16x32_bf16 v[10:13], v[160:163], v[220:223], v[10:13]
	v_mfma_f32_16x16x32_bf16 v[54:57], v[164:167], v[180:183], v[54:57]
	v_mfma_f32_16x16x32_bf16 v[50:53], v[172:175], v[180:183], v[50:53]
	v_mfma_f32_16x16x32_bf16 v[38:41], v[164:167], v[188:191], v[38:41]
	v_mfma_f32_16x16x32_bf16 v[34:37], v[172:175], v[188:191], v[34:37]
	v_mfma_f32_16x16x32_bf16 v[22:25], v[164:167], v[196:199], v[22:25]
	v_mfma_f32_16x16x32_bf16 v[18:21], v[172:175], v[196:199], v[18:21]
	v_mfma_f32_16x16x32_bf16 v[6:9], v[164:167], v[204:207], v[6:9]
	v_mfma_f32_16x16x32_bf16 v[2:5], v[172:175], v[204:207], v[2:5]
	v_mfma_f32_16x16x32_bf16 v[54:57], v[168:171], v[184:187], v[54:57]
	v_mfma_f32_16x16x32_bf16 v[50:53], v[176:179], v[184:187], v[50:53]
	v_mfma_f32_16x16x32_bf16 v[38:41], v[168:171], v[192:195], v[38:41]
	v_mfma_f32_16x16x32_bf16 v[34:37], v[176:179], v[192:195], v[34:37]
	v_mfma_f32_16x16x32_bf16 v[22:25], v[168:171], v[200:203], v[22:25]
	v_mfma_f32_16x16x32_bf16 v[18:21], v[176:179], v[200:203], v[18:21]
	v_mfma_f32_16x16x32_bf16 v[6:9], v[168:171], v[220:223], v[6:9]
	v_mfma_f32_16x16x32_bf16 v[2:5], v[176:179], v[220:223], v[2:5]
	s_barrier
	s_add_i32 s31, 0, 0x18000
	s_add_i32 s64, 0, 0x1c000
	v_add_u32_e32 v160, s31, v146
	v_add_u32_e32 v176, s64, v146
	ds_read_b128 v[148:151], v160
	ds_read_b128 v[152:155], v160 offset:1024
	ds_read_b128 v[156:159], v160 offset:2048
	ds_read_b128 v[160:163], v160 offset:3072
	ds_read_b128 v[164:167], v176
	ds_read_b128 v[168:171], v176 offset:1024
	ds_read_b128 v[172:175], v176 offset:2048
	ds_read_b128 v[176:179], v176 offset:3072
	s_add_u32 s38, s38, s45
	s_addc_u32 s39, s39, 0
	s_mov_b32 m0, s53
	v_lshl_add_u64 v[242:243], s[38:39], 0, v[130:131]
	ds_read_b128 v[180:183], v147 offset:32768
	ds_read_b128 v[184:187], v147 offset:33792
	ds_read_b128 v[188:191], v147 offset:34816
	ds_read_b128 v[192:195], v147 offset:35840
	ds_read_b128 v[196:199], v147 offset:36864
	ds_read_b128 v[200:203], v147 offset:37888
	ds_read_b128 v[204:207], v147 offset:38912
	ds_read_b128 v[220:223], v147 offset:39936
	global_load_lds_dwordx4 v[242:243], off
	v_lshl_add_u64 v[242:243], s[38:39], 0, v[134:135]
	s_mov_b32 m0, s54
	s_nop 0
	global_load_lds_dwordx4 v[242:243], off
	s_nop 0
	s_nop 0
	s_nop 0
	s_nop 0
	s_nop 0
	s_nop 0
	s_nop 0
	s_nop 0
	s_waitcnt vmcnt(8)
	s_waitcnt lgkmcnt(0)
	s_barrier
	s_waitcnt lgkmcnt(0)
	v_mfma_f32_16x16x32_bf16 v[126:129], v[148:151], v[180:183], v[126:129]
	v_mfma_f32_16x16x32_bf16 v[122:125], v[156:159], v[180:183], v[122:125]
	v_mfma_f32_16x16x32_bf16 v[110:113], v[148:151], v[188:191], v[110:113]
	v_mfma_f32_16x16x32_bf16 v[106:109], v[156:159], v[188:191], v[106:109]
	v_mfma_f32_16x16x32_bf16 v[94:97], v[148:151], v[196:199], v[94:97]
	v_mfma_f32_16x16x32_bf16 v[90:93], v[156:159], v[196:199], v[90:93]
	v_mfma_f32_16x16x32_bf16 v[78:81], v[148:151], v[204:207], v[78:81]
	v_mfma_f32_16x16x32_bf16 v[74:77], v[156:159], v[204:207], v[74:77]
	v_mfma_f32_16x16x32_bf16 v[126:129], v[152:155], v[184:187], v[126:129]
	v_mfma_f32_16x16x32_bf16 v[122:125], v[160:163], v[184:187], v[122:125]
	v_mfma_f32_16x16x32_bf16 v[110:113], v[152:155], v[192:195], v[110:113]
	v_mfma_f32_16x16x32_bf16 v[106:109], v[160:163], v[192:195], v[106:109]
	v_mfma_f32_16x16x32_bf16 v[94:97], v[152:155], v[200:203], v[94:97]
	v_mfma_f32_16x16x32_bf16 v[90:93], v[160:163], v[200:203], v[90:93]
	v_mfma_f32_16x16x32_bf16 v[78:81], v[152:155], v[220:223], v[78:81]
	v_mfma_f32_16x16x32_bf16 v[74:77], v[160:163], v[220:223], v[74:77]
	v_mfma_f32_16x16x32_bf16 v[118:121], v[164:167], v[180:183], v[118:121]
	v_mfma_f32_16x16x32_bf16 v[114:117], v[172:175], v[180:183], v[114:117]
	v_mfma_f32_16x16x32_bf16 v[102:105], v[164:167], v[188:191], v[102:105]
	v_mfma_f32_16x16x32_bf16 v[98:101], v[172:175], v[188:191], v[98:101]
	v_mfma_f32_16x16x32_bf16 v[86:89], v[164:167], v[196:199], v[86:89]
	v_mfma_f32_16x16x32_bf16 v[82:85], v[172:175], v[196:199], v[82:85]
	v_mfma_f32_16x16x32_bf16 v[70:73], v[164:167], v[204:207], v[70:73]
	v_mfma_f32_16x16x32_bf16 v[66:69], v[172:175], v[204:207], v[66:69]
	v_mfma_f32_16x16x32_bf16 v[118:121], v[168:171], v[184:187], v[118:121]
	v_mfma_f32_16x16x32_bf16 v[114:117], v[176:179], v[184:187], v[114:117]
	v_mfma_f32_16x16x32_bf16 v[102:105], v[168:171], v[192:195], v[102:105]
	v_mfma_f32_16x16x32_bf16 v[98:101], v[176:179], v[192:195], v[98:101]
	v_mfma_f32_16x16x32_bf16 v[86:89], v[168:171], v[200:203], v[86:89]
	v_mfma_f32_16x16x32_bf16 v[82:85], v[176:179], v[200:203], v[82:85]
	v_mfma_f32_16x16x32_bf16 v[70:73], v[168:171], v[220:223], v[70:73]
	v_mfma_f32_16x16x32_bf16 v[66:69], v[176:179], v[220:223], v[66:69]
	s_barrier
	s_add_i32 s31, s31, s47
	v_lshl_add_u64 v[208:209], v[208:209], 0, s[96:97]
	s_mov_b32 m0, s31
	ds_read_b128 v[180:183], v147 offset:49152
	ds_read_b128 v[184:187], v147 offset:50176
	ds_read_b128 v[188:191], v147 offset:51200
	ds_read_b128 v[192:195], v147 offset:52224
	ds_read_b128 v[196:199], v147 offset:53248
	ds_read_b128 v[200:203], v147 offset:54272
	ds_read_b128 v[204:207], v147 offset:55296
	ds_read_b128 v[220:223], v147 offset:56320
	global_load_lds_dwordx4 v[208:209], off
	v_lshl_add_u64 v[208:209], v[224:225], 0, s[96:97]
	s_add_i32 m0, s31, 0x2000
	s_add_i32 s31, s64, s47
	global_load_lds_dwordx4 v[208:209], off
	v_lshl_add_u64 v[208:209], v[230:231], 0, s[96:97]
	s_mov_b32 m0, s31
	s_nop 0
	global_load_lds_dwordx4 v[208:209], off
	v_lshl_add_u64 v[208:209], v[236:237], 0, s[96:97]
	s_add_i32 m0, s31, 0x2000
	s_nop 0
	global_load_lds_dwordx4 v[208:209], off
	v_lshl_add_u64 v[208:209], v[238:239], 0, s[96:97]
	s_mov_b32 m0, s57
	s_nop 0
	global_load_lds_dwordx4 v[208:209], off
	v_lshl_add_u64 v[208:209], v[240:241], 0, s[96:97]
	s_mov_b32 m0, s58
	s_nop 0
	global_load_lds_dwordx4 v[208:209], off
	s_nop 0
	s_nop 0
	s_nop 0
	s_nop 0
	s_nop 0
	s_waitcnt vmcnt(8)
	s_waitcnt lgkmcnt(0)
	s_barrier
	s_waitcnt lgkmcnt(0)
	v_mfma_f32_16x16x32_bf16 v[62:65], v[148:151], v[180:183], v[62:65]
	v_mfma_f32_16x16x32_bf16 v[58:61], v[156:159], v[180:183], v[58:61]
	v_mfma_f32_16x16x32_bf16 v[46:49], v[148:151], v[188:191], v[46:49]
	v_mfma_f32_16x16x32_bf16 v[42:45], v[156:159], v[188:191], v[42:45]
	v_mfma_f32_16x16x32_bf16 v[30:33], v[148:151], v[196:199], v[30:33]
	v_mfma_f32_16x16x32_bf16 v[26:29], v[156:159], v[196:199], v[26:29]
	v_mfma_f32_16x16x32_bf16 v[14:17], v[148:151], v[204:207], v[14:17]
	v_mfma_f32_16x16x32_bf16 v[10:13], v[156:159], v[204:207], v[10:13]
	v_mfma_f32_16x16x32_bf16 v[62:65], v[152:155], v[184:187], v[62:65]
	v_mfma_f32_16x16x32_bf16 v[58:61], v[160:163], v[184:187], v[58:61]
	v_mfma_f32_16x16x32_bf16 v[46:49], v[152:155], v[192:195], v[46:49]
	v_mfma_f32_16x16x32_bf16 v[42:45], v[160:163], v[192:195], v[42:45]
	v_mfma_f32_16x16x32_bf16 v[30:33], v[152:155], v[200:203], v[30:33]
	v_mfma_f32_16x16x32_bf16 v[26:29], v[160:163], v[200:203], v[26:29]
	v_mfma_f32_16x16x32_bf16 v[14:17], v[152:155], v[220:223], v[14:17]
	v_mfma_f32_16x16x32_bf16 v[10:13], v[160:163], v[220:223], v[10:13]
	v_mfma_f32_16x16x32_bf16 v[54:57], v[164:167], v[180:183], v[54:57]
	v_mfma_f32_16x16x32_bf16 v[50:53], v[172:175], v[180:183], v[50:53]
	v_mfma_f32_16x16x32_bf16 v[38:41], v[164:167], v[188:191], v[38:41]
	v_mfma_f32_16x16x32_bf16 v[34:37], v[172:175], v[188:191], v[34:37]
	v_mfma_f32_16x16x32_bf16 v[22:25], v[164:167], v[196:199], v[22:25]
	v_mfma_f32_16x16x32_bf16 v[18:21], v[172:175], v[196:199], v[18:21]
	v_mfma_f32_16x16x32_bf16 v[6:9], v[164:167], v[204:207], v[6:9]
	v_mfma_f32_16x16x32_bf16 v[2:5], v[172:175], v[204:207], v[2:5]
	v_mfma_f32_16x16x32_bf16 v[54:57], v[168:171], v[184:187], v[54:57]
	v_mfma_f32_16x16x32_bf16 v[50:53], v[176:179], v[184:187], v[50:53]
	v_mfma_f32_16x16x32_bf16 v[38:41], v[168:171], v[192:195], v[38:41]
	v_mfma_f32_16x16x32_bf16 v[34:37], v[176:179], v[192:195], v[34:37]
	v_mfma_f32_16x16x32_bf16 v[22:25], v[168:171], v[200:203], v[22:25]
	v_mfma_f32_16x16x32_bf16 v[18:21], v[176:179], v[200:203], v[18:21]
	v_mfma_f32_16x16x32_bf16 v[6:9], v[168:171], v[220:223], v[6:9]
	v_mfma_f32_16x16x32_bf16 v[2:5], v[176:179], v[220:223], v[2:5]
	s_barrier
	s_add_u32 s36, s36, 0x100
	s_addc_u32 s37, s37, 0
	v_lshl_add_u64 v[144:145], v[144:145], 0, s[2:3]
	v_lshl_add_u64 v[142:143], v[142:143], 0, s[2:3]
	s_cmp_ge_u32 s63, s56
	s_mov_b32 s31, s63
	s_cbranch_scc0 .LBB0_476
	s_and_b64 vcc, exec, s[6:7]
	s_cbranch_vccnz .LBB0_464
	v_mov_b32_e32 v2, 0
	s_mov_b32 s55, s61
	s_mov_b32 s50, s62
	s_mov_b64 s[26:27], s[34:35]
	s_mov_b64 s[28:29], s[8:9]
	s_mov_b32 s60, s30
	v_mov_b32_e32 v3, v2
	v_mov_b32_e32 v4, v2
	v_mov_b32_e32 v5, v2
	v_mov_b32_e32 v6, v2
	v_mov_b32_e32 v7, v2
	v_mov_b32_e32 v8, v2
	v_mov_b32_e32 v9, v2
	v_mov_b32_e32 v18, v2
	v_mov_b32_e32 v19, v2
	v_mov_b32_e32 v20, v2
	v_mov_b32_e32 v21, v2
	v_mov_b32_e32 v22, v2
	v_mov_b32_e32 v23, v2
	v_mov_b32_e32 v24, v2
	v_mov_b32_e32 v25, v2
	v_mov_b32_e32 v34, v2
	v_mov_b32_e32 v35, v2
	v_mov_b32_e32 v36, v2
	v_mov_b32_e32 v37, v2
	v_mov_b32_e32 v38, v2
	v_mov_b32_e32 v39, v2
	v_mov_b32_e32 v40, v2
	v_mov_b32_e32 v41, v2
	v_mov_b32_e32 v50, v2
	v_mov_b32_e32 v51, v2
	v_mov_b32_e32 v52, v2
	v_mov_b32_e32 v53, v2
	v_mov_b32_e32 v54, v2
	v_mov_b32_e32 v55, v2
	v_mov_b32_e32 v56, v2
	v_mov_b32_e32 v57, v2
	v_mov_b32_e32 v10, v2
	v_mov_b32_e32 v11, v2
	v_mov_b32_e32 v12, v2
	v_mov_b32_e32 v13, v2
	v_mov_b32_e32 v14, v2
	v_mov_b32_e32 v15, v2
	v_mov_b32_e32 v16, v2
	v_mov_b32_e32 v17, v2
	v_mov_b32_e32 v26, v2
	v_mov_b32_e32 v27, v2
	v_mov_b32_e32 v28, v2
	v_mov_b32_e32 v29, v2
	v_mov_b32_e32 v30, v2
	v_mov_b32_e32 v31, v2
	v_mov_b32_e32 v32, v2
	v_mov_b32_e32 v33, v2
	v_mov_b32_e32 v42, v2
	v_mov_b32_e32 v43, v2
	v_mov_b32_e32 v44, v2
	v_mov_b32_e32 v45, v2
	v_mov_b32_e32 v46, v2
	v_mov_b32_e32 v47, v2
	v_mov_b32_e32 v48, v2
	v_mov_b32_e32 v49, v2
	v_mov_b32_e32 v58, v2
	v_mov_b32_e32 v59, v2
	v_mov_b32_e32 v60, v2
	v_mov_b32_e32 v61, v2
	v_mov_b32_e32 v62, v2
	v_mov_b32_e32 v63, v2
	v_mov_b32_e32 v64, v2
	v_mov_b32_e32 v65, v2
	v_mov_b32_e32 v66, v2
	v_mov_b32_e32 v67, v2
	v_mov_b32_e32 v68, v2
	v_mov_b32_e32 v69, v2
	v_mov_b32_e32 v70, v2
	v_mov_b32_e32 v71, v2
	v_mov_b32_e32 v72, v2
	v_mov_b32_e32 v73, v2
	v_mov_b32_e32 v82, v2
	v_mov_b32_e32 v83, v2
	v_mov_b32_e32 v84, v2
	v_mov_b32_e32 v85, v2
	v_mov_b32_e32 v86, v2
	v_mov_b32_e32 v87, v2
	v_mov_b32_e32 v88, v2
	v_mov_b32_e32 v89, v2
	v_mov_b32_e32 v98, v2
	v_mov_b32_e32 v99, v2
	v_mov_b32_e32 v100, v2
	v_mov_b32_e32 v101, v2
	v_mov_b32_e32 v102, v2
	v_mov_b32_e32 v103, v2
	v_mov_b32_e32 v104, v2
	v_mov_b32_e32 v105, v2
	v_mov_b32_e32 v114, v2
	v_mov_b32_e32 v115, v2
	v_mov_b32_e32 v116, v2
	v_mov_b32_e32 v117, v2
	v_mov_b32_e32 v118, v2
	v_mov_b32_e32 v119, v2
	v_mov_b32_e32 v120, v2
	v_mov_b32_e32 v121, v2
	v_mov_b32_e32 v74, v2
	v_mov_b32_e32 v75, v2
	v_mov_b32_e32 v76, v2
	v_mov_b32_e32 v77, v2
	v_mov_b32_e32 v78, v2
	v_mov_b32_e32 v79, v2
	v_mov_b32_e32 v80, v2
	v_mov_b32_e32 v81, v2
	v_mov_b32_e32 v90, v2
	v_mov_b32_e32 v91, v2
	v_mov_b32_e32 v92, v2
	v_mov_b32_e32 v93, v2
	v_mov_b32_e32 v94, v2
	v_mov_b32_e32 v95, v2
	v_mov_b32_e32 v96, v2
	v_mov_b32_e32 v97, v2
	v_mov_b32_e32 v106, v2
	v_mov_b32_e32 v107, v2
	v_mov_b32_e32 v108, v2
	v_mov_b32_e32 v109, v2
	v_mov_b32_e32 v110, v2
	v_mov_b32_e32 v111, v2
	v_mov_b32_e32 v112, v2
	v_mov_b32_e32 v113, v2
	v_mov_b32_e32 v122, v2
	v_mov_b32_e32 v123, v2
	v_mov_b32_e32 v124, v2
	v_mov_b32_e32 v125, v2
	v_mov_b32_e32 v126, v2
	v_mov_b32_e32 v127, v2
	v_mov_b32_e32 v128, v2
	v_mov_b32_e32 v129, v2
	s_branch .LBB0_464
